# non-temporal cache hint (nt) on read-once / write-once streams: P0 f32 input loads, P4 residual loads, P7 epilogue base loads and final output stores
# speedup vs baseline: 1.0024x; 1.0015x over previous
.LBB0_13:
	s_cmpk_gt_i32 s79, 0x3fff
	s_mov_b64 s[0:1], -1
	s_cbranch_scc0 .LBB0_35
	s_cmpk_gt_u32 s79, 0x4fff
	s_cbranch_scc0 .LBB0_30
	s_cmpk_gt_u32 s79, 0x6fff
	s_cbranch_scc0 .LBB0_25
	s_cmpk_gt_u32 s79, 0x7fff
	s_cbranch_scc0 .LBB0_20
	s_add_i32 s1, s79, 0xffff8000
	s_and_b32 s0, s1, 0xffffffc0
	v_add_u32_e32 v0, s0, v69
	s_lshl_b32 s1, s1, 8
	s_and_b32 s14, s1, 0x3f00
	v_ashrrev_i32_e32 v1, 31, v0
	v_lshl_add_u64 v[2:3], v[72:73], 0, s[14:15]
	v_lshlrev_b64 v[0:1], 14, v[0:1]
	v_lshl_add_u64 v[0:1], v[2:3], 0, v[0:1]
	v_add_co_u32_e32 v2, vcc, 0x10000, v0
	s_and_b32 s1, s13, 0x7ffff000
	s_nop 0
	v_addc_co_u32_e32 v3, vcc, 0, v1, vcc
	global_load_dwordx4 v[4:7], v[0:1], off nt
	global_load_dwordx4 v[8:11], v[2:3], off nt
	v_add_co_u32_e32 v2, vcc, 0x20000, v0
	s_movk_i32 s14, 0xffc0
	s_nop 0
	v_addc_co_u32_e32 v3, vcc, 0, v1, vcc
	v_add_co_u32_e32 v16, vcc, 0x30000, v0
	s_nop 1
	v_addc_co_u32_e32 v17, vcc, 0, v1, vcc
	global_load_dwordx4 v[12:15], v[2:3], off nt
	s_nop 0
	global_load_dwordx4 v[16:19], v[16:17], off nt
	v_add_co_u32_e32 v2, vcc, 0x40000, v0
	s_nop 1
	v_addc_co_u32_e32 v3, vcc, 0, v1, vcc
	v_add_co_u32_e32 v24, vcc, 0x50000, v0
	s_nop 1
	v_addc_co_u32_e32 v25, vcc, 0, v1, vcc
	global_load_dwordx4 v[20:23], v[2:3], off nt
	s_nop 0
	global_load_dwordx4 v[24:27], v[24:25], off nt
	v_add_co_u32_e32 v2, vcc, 0x60000, v0
	s_nop 1
	v_addc_co_u32_e32 v3, vcc, 0, v1, vcc
	v_add_co_u32_e32 v32, vcc, 0x70000, v0
	s_nop 1
	v_addc_co_u32_e32 v33, vcc, 0, v1, vcc
	global_load_dwordx4 v[28:31], v[2:3], off nt
	s_nop 0
	global_load_dwordx4 v[32:35], v[32:33], off nt
	v_add_co_u32_e32 v2, vcc, 0x80000, v0
	s_nop 1
	v_addc_co_u32_e32 v3, vcc, 0, v1, vcc
	v_add_co_u32_e32 v40, vcc, 0x90000, v0
	s_nop 1
	v_addc_co_u32_e32 v41, vcc, 0, v1, vcc
	global_load_dwordx4 v[36:39], v[2:3], off nt
	s_nop 0
	global_load_dwordx4 v[40:43], v[40:41], off nt
	v_add_co_u32_e32 v2, vcc, 0xa0000, v0
	s_nop 1
	v_addc_co_u32_e32 v3, vcc, 0, v1, vcc
	v_add_co_u32_e32 v48, vcc, 0xb0000, v0
	s_nop 1
	v_addc_co_u32_e32 v49, vcc, 0, v1, vcc
	global_load_dwordx4 v[44:47], v[2:3], off nt
	s_nop 0
	global_load_dwordx4 v[48:51], v[48:49], off nt
	v_add_co_u32_e32 v2, vcc, 0xc0000, v0
	s_nop 1
	v_addc_co_u32_e32 v3, vcc, 0, v1, vcc
	v_add_co_u32_e32 v56, vcc, 0xd0000, v0
	s_nop 1
	v_addc_co_u32_e32 v57, vcc, 0, v1, vcc
	global_load_dwordx4 v[52:55], v[2:3], off nt
	s_nop 0
	global_load_dwordx4 v[56:59], v[56:57], off nt
	v_add_co_u32_e32 v2, vcc, 0xe0000, v0
	s_nop 1
	v_addc_co_u32_e32 v3, vcc, 0, v1, vcc
	global_load_dwordx4 v[60:63], v[2:3], off nt
	v_add_co_u32_e32 v0, vcc, 0xf0000, v0
	s_nop 1
	v_addc_co_u32_e32 v1, vcc, 0, v1, vcc
	global_load_dwordx4 v[64:67], v[0:1], off nt
	v_add_u32_e32 v0, 0x30c8, v97
	v_subrev_u32_e32 v2, s1, v101
	s_mov_b32 s1, s15
	v_mov_b32_e32 v3, v102
	s_waitcnt vmcnt(15)
	ds_write2_b32 v97, v4, v5 offset1:1
	ds_write2_b32 v97, v6, v7 offset0:2 offset1:3
	s_waitcnt vmcnt(14)
	ds_write2_b32 v104, v8, v9 offset1:1
	ds_write2_b32 v105, v10, v11 offset1:1
	s_waitcnt vmcnt(13)
	ds_write2_b32 v106, v12, v13 offset1:1
	ds_write2_b32 v107, v14, v15 offset1:1
	s_waitcnt vmcnt(12)
	ds_write2_b32 v108, v16, v17 offset1:1
	ds_write2_b32 v109, v18, v19 offset1:1
	s_waitcnt vmcnt(11)
	ds_write2_b32 v110, v20, v21 offset1:1
	ds_write2_b32 v111, v22, v23 offset1:1
	s_waitcnt vmcnt(10)
	ds_write2_b32 v112, v24, v25 offset1:1
	ds_write2_b32 v113, v26, v27 offset1:1
	s_waitcnt vmcnt(9)
	ds_write2_b32 v114, v28, v29 offset1:1
	ds_write2_b32 v115, v30, v31 offset1:1
	s_waitcnt vmcnt(8)
	ds_write2_b32 v116, v32, v33 offset1:1
	ds_write2_b32 v117, v34, v35 offset1:1
	s_waitcnt vmcnt(7)
	ds_write2_b32 v118, v36, v37 offset1:1
	ds_write2_b32 v119, v38, v39 offset1:1
	s_waitcnt vmcnt(6)
	ds_write2_b32 v120, v40, v41 offset1:1
	ds_write2_b32 v123, v42, v43 offset1:1
	s_waitcnt vmcnt(5)
	ds_write2_b32 v124, v44, v45 offset1:1
	ds_write2_b32 v125, v46, v47 offset1:1
	s_waitcnt vmcnt(4)
	ds_write2_b32 v126, v48, v49 offset1:1
	ds_write2_b32 v127, v50, v51 offset1:1
	s_waitcnt vmcnt(3)
	ds_write2_b32 v128, v52, v53 offset1:1
	ds_write2_b32 v0, v54, v55 offset1:1
	v_add_u32_e32 v0, 0x34d0, v97
	s_waitcnt vmcnt(2)
	ds_write2_b32 v0, v56, v57 offset1:1
	v_add_u32_e32 v0, 0x34d8, v97
	ds_write2_b32 v0, v58, v59 offset1:1
	v_add_u32_e32 v0, 0x38e0, v97
	s_waitcnt vmcnt(1)
	ds_write2_b32 v0, v60, v61 offset1:1
	v_add_u32_e32 v0, 0x38e8, v97
	ds_write2_b32 v0, v62, v63 offset1:1
	v_add_u32_e32 v0, 0x3cf0, v97
	s_waitcnt vmcnt(0)
	ds_write2_b32 v0, v64, v65 offset1:1
	v_add_u32_e32 v0, 0x3cf8, v97
	ds_write2_b32 v0, v66, v67 offset1:1
	s_waitcnt lgkmcnt(0)
	v_lshl_add_u64 v[0:1], s[0:1], 1, v[74:75]

.LBB0_20:
	s_and_b64 vcc, exec, s[0:1]
	s_cbranch_vccz .LBB0_24
	s_lshr_b32 s14, s22, 10
	s_lshl_b64 s[0:1], s[14:15], 23
	s_lshl_b32 s14, s23, 1
	s_and_b32 s21, s14, 0xf80
	s_add_i32 s14, s79, 0xffff9000
	s_lshr_b32 s14, s14, 10
	s_and_b32 s20, s11, 0x7c0
	s_lshl_b64 s[18:19], s[14:15], 24
	s_add_u32 s14, s58, s18
	s_addc_u32 s19, s59, s19
	s_lshl_b32 s18, s79, 1
	s_and_b32 s18, s18, 0x7c0
	v_add_u32_e32 v0, s18, v69
	s_lshl_b32 s18, s79, 8
	s_and_b32 s18, s18, 0x1f00
	s_add_u32 s18, s14, s18
	s_addc_u32 s19, s19, 0
	v_mov_b32_e32 v89, v71
	v_ashrrev_i32_e32 v1, 31, v0
	v_lshl_add_u64 v[2:3], s[18:19], 0, v[88:89]
	v_lshlrev_b64 v[0:1], 13, v[0:1]
	v_lshl_add_u64 v[0:1], v[2:3], 0, v[0:1]
	v_add_co_u32_e32 v2, vcc, s38, v0
	s_nop 1
	v_addc_co_u32_e32 v3, vcc, 0, v1, vcc
	global_load_dwordx4 v[4:7], v[0:1], off nt
	global_load_dwordx4 v[8:11], v[2:3], off nt
	v_add_co_u32_e32 v2, vcc, s27, v0
	s_nop 1
	v_addc_co_u32_e32 v3, vcc, 0, v1, vcc
	v_add_co_u32_e32 v16, vcc, s39, v0
	s_nop 1
	v_addc_co_u32_e32 v17, vcc, 0, v1, vcc
	global_load_dwordx4 v[12:15], v[2:3], off nt
	s_nop 0
	global_load_dwordx4 v[16:19], v[16:17], off nt
	v_add_co_u32_e32 v2, vcc, s28, v0
	s_nop 1
	v_addc_co_u32_e32 v3, vcc, 0, v1, vcc
	v_add_co_u32_e32 v24, vcc, s48, v0
	s_nop 1
	v_addc_co_u32_e32 v25, vcc, 0, v1, vcc
	global_load_dwordx4 v[20:23], v[2:3], off nt
	s_nop 0
	global_load_dwordx4 v[24:27], v[24:25], off nt
	v_add_co_u32_e32 v2, vcc, s29, v0
	s_nop 1
	v_addc_co_u32_e32 v3, vcc, 0, v1, vcc
	v_add_co_u32_e32 v32, vcc, s49, v0
	s_nop 1
	v_addc_co_u32_e32 v33, vcc, 0, v1, vcc
	global_load_dwordx4 v[28:31], v[2:3], off nt
	s_nop 0
	global_load_dwordx4 v[32:35], v[32:33], off nt
	v_add_co_u32_e32 v2, vcc, s30, v0
	s_nop 1
	v_addc_co_u32_e32 v3, vcc, 0, v1, vcc
	v_add_co_u32_e32 v40, vcc, s54, v0
	s_nop 1
	v_addc_co_u32_e32 v41, vcc, 0, v1, vcc
	global_load_dwordx4 v[36:39], v[2:3], off nt
	s_nop 0
	global_load_dwordx4 v[40:43], v[40:41], off nt
	v_add_co_u32_e32 v2, vcc, s31, v0
	s_nop 1
	v_addc_co_u32_e32 v3, vcc, 0, v1, vcc
	v_add_co_u32_e32 v48, vcc, s55, v0
	s_nop 1
	v_addc_co_u32_e32 v49, vcc, 0, v1, vcc
	global_load_dwordx4 v[44:47], v[2:3], off nt
	s_nop 0
	global_load_dwordx4 v[48:51], v[48:49], off nt
	v_add_co_u32_e32 v2, vcc, s34, v0
	s_nop 1
	v_addc_co_u32_e32 v3, vcc, 0, v1, vcc
	global_load_dwordx4 v[52:55], v[2:3], off nt
	v_add_co_u32_e32 v2, vcc, s62, v0
	s_nop 1
	v_addc_co_u32_e32 v3, vcc, 0, v1, vcc
	global_load_dwordx4 v[56:59], v[2:3], off nt
	v_add_co_u32_e32 v2, vcc, s35, v0
	s_nop 1
	v_addc_co_u32_e32 v3, vcc, 0, v1, vcc
	global_load_dwordx4 v[60:63], v[2:3], off nt
	v_add_co_u32_e32 v0, vcc, s63, v0
	s_nop 1
	v_addc_co_u32_e32 v1, vcc, 0, v1, vcc
	global_load_dwordx4 v[64:67], v[0:1], off nt
	v_add_u32_e32 v0, s20, v103
	v_add_u32_e32 v2, s20, v98
	v_ashrrev_i32_e32 v1, 31, v0
	v_ashrrev_i32_e32 v3, 31, v2
	v_lshlrev_b64 v[0:1], 12, v[0:1]
	v_lshlrev_b64 v[2:3], 12, v[2:3]
	v_lshl_add_u64 v[0:1], s[0:1], 0, v[0:1]
	v_lshl_add_u64 v[2:3], s[0:1], 0, v[2:3]
	v_or_b32_e32 v0, s21, v0
	s_waitcnt vmcnt(15)
	ds_write2_b32 v97, v4, v5 offset1:1
	ds_write2_b32 v97, v6, v7 offset0:2 offset1:3
	s_waitcnt vmcnt(14)
	ds_write2_b32 v104, v8, v9 offset1:1
	ds_write2_b32 v105, v10, v11 offset1:1
	s_waitcnt vmcnt(13)
	ds_write2_b32 v106, v12, v13 offset1:1
	ds_write2_b32 v107, v14, v15 offset1:1
	s_waitcnt vmcnt(12)
	ds_write2_b32 v108, v16, v17 offset1:1
	ds_write2_b32 v109, v18, v19 offset1:1
	s_waitcnt vmcnt(11)
	ds_write2_b32 v110, v20, v21 offset1:1
	ds_write2_b32 v111, v22, v23 offset1:1
	s_waitcnt vmcnt(10)
	ds_write2_b32 v112, v24, v25 offset1:1
	ds_write2_b32 v113, v26, v27 offset1:1
	s_waitcnt vmcnt(9)
	ds_write2_b32 v114, v28, v29 offset1:1
	ds_write2_b32 v115, v30, v31 offset1:1
	s_waitcnt vmcnt(8)
	ds_write2_b32 v116, v32, v33 offset1:1
	ds_write2_b32 v117, v34, v35 offset1:1
	s_waitcnt vmcnt(7)
	ds_write2_b32 v118, v36, v37 offset1:1
	ds_write2_b32 v119, v38, v39 offset1:1
	s_waitcnt vmcnt(6)
	ds_write2_b32 v120, v40, v41 offset1:1
	ds_write2_b32 v123, v42, v43 offset1:1
	s_waitcnt vmcnt(5)
	ds_write2_b32 v124, v44, v45 offset1:1
	ds_write2_b32 v125, v46, v47 offset1:1
	s_waitcnt vmcnt(4)
	ds_write2_b32 v126, v48, v49 offset1:1
	ds_write2_b32 v127, v50, v51 offset1:1
	s_waitcnt vmcnt(3)
	ds_write2_b32 v128, v52, v53 offset1:1
	v_add_u32_e32 v4, 0x30c8, v97
	v_or_b32_e32 v2, s21, v2
	v_lshl_add_u64 v[0:1], v[86:87], 0, v[0:1]
	v_lshl_add_u64 v[2:3], v[86:87], 0, v[2:3]
	s_mov_b64 s[0:1], 0
	ds_write2_b32 v4, v54, v55 offset1:1
	v_add_u32_e32 v4, 0x34d0, v97
	s_waitcnt vmcnt(2)
	ds_write2_b32 v4, v56, v57 offset1:1
	v_add_u32_e32 v4, 0x34d8, v97
	ds_write2_b32 v4, v58, v59 offset1:1
	v_add_u32_e32 v4, 0x38e0, v97
	s_waitcnt vmcnt(1)
	ds_write2_b32 v4, v60, v61 offset1:1
	v_add_u32_e32 v4, 0x38e8, v97
	ds_write2_b32 v4, v62, v63 offset1:1
	v_add_u32_e32 v4, 0x3cf0, v97
	s_waitcnt vmcnt(0)
	ds_write2_b32 v4, v64, v65 offset1:1
	v_add_u32_e32 v4, 0x3cf8, v97
	ds_write2_b32 v4, v66, v67 offset1:1
	s_waitcnt lgkmcnt(0)
	v_mov_b32_e32 v4, v102

.LBB0_25:
	s_andn2_b64 vcc, exec, s[0:1]
	s_cbranch_vccnz .LBB0_29
	s_lshl_b32 s0, s25, 6
	s_and_b32 s0, s0, 0xffffe000
	s_lshl_b32 s1, s79, 19
	v_subrev_u32_e32 v20, s0, v101
	s_add_i32 s0, s79, 0xffffb000
	s_and_b32 s1, s1, 0x3f00000
	s_add_u32 s1, s76, s1
	s_addc_u32 s14, s77, 0
	s_lshr_b32 s19, s0, 7
	s_lshl_b32 s18, s19, 13
	s_lshl_b32 s20, s0, 6
	v_lshl_add_u32 v18, s19, 6, v69
	s_sub_i32 s18, s20, s18
	v_add_u32_e32 v30, 4, v18
	s_ashr_i32 s19, s18, 31
	v_ashrrev_i32_e32 v19, 31, v18
	v_ashrrev_i32_e32 v31, 31, v30
	v_lshl_add_u64 v[16:17], s[18:19], 2, v[76:77]
	v_lshlrev_b64 v[0:1], 16, v[18:19]
	v_lshlrev_b64 v[2:3], 16, v[30:31]
	v_add_u32_e32 v32, 8, v18
	v_add_u32_e32 v38, 12, v18
	v_lshl_add_u64 v[0:1], v[16:17], 0, v[0:1]
	v_lshl_add_u64 v[2:3], v[16:17], 0, v[2:3]
	v_ashrrev_i32_e32 v33, 31, v32
	v_ashrrev_i32_e32 v39, 31, v38
	global_load_dwordx4 v[12:15], v[0:1], off nt
	global_load_dwordx4 v[8:11], v[2:3], off nt
	v_lshlrev_b64 v[0:1], 16, v[32:33]
	v_lshlrev_b64 v[2:3], 16, v[38:39]
	v_add_u32_e32 v40, 16, v18
	v_add_u32_e32 v42, 20, v18
	v_lshl_add_u64 v[0:1], v[16:17], 0, v[0:1]
	v_lshl_add_u64 v[2:3], v[16:17], 0, v[2:3]
	v_ashrrev_i32_e32 v41, 31, v40
	v_ashrrev_i32_e32 v43, 31, v42
	v_lshl_add_u64 v[26:27], v[18:19], 2, s[4:5]
	global_load_dwordx4 v[4:7], v[0:1], off nt
	s_nop 0
	global_load_dwordx4 v[0:3], v[2:3], off nt
	v_lshlrev_b64 v[22:23], 16, v[40:41]
	v_lshlrev_b64 v[24:25], 16, v[42:43]
	global_load_dword v66, v[26:27], off
	v_lshl_add_u64 v[22:23], v[16:17], 0, v[22:23]
	v_lshl_add_u64 v[26:27], v[16:17], 0, v[24:25]
	v_lshl_add_u64 v[30:31], v[30:31], 2, s[4:5]
	global_load_dwordx4 v[22:25], v[22:23], off nt
	s_nop 0
	global_load_dwordx4 v[26:29], v[26:27], off nt
	v_add_u32_e32 v46, 24, v18
	global_load_dword v90, v[30:31], off
	v_add_u32_e32 v48, 28, v18
	v_ashrrev_i32_e32 v47, 31, v46
	v_ashrrev_i32_e32 v49, 31, v48
	v_lshl_add_u64 v[32:33], v[32:33], 2, s[4:5]
	global_load_dword v92, v[32:33], off
	v_lshlrev_b64 v[30:31], 16, v[46:47]
	v_lshlrev_b64 v[32:33], 16, v[48:49]
	v_lshl_add_u64 v[30:31], v[16:17], 0, v[30:31]
	v_lshl_add_u64 v[34:35], v[16:17], 0, v[32:33]
	v_lshl_add_u64 v[38:39], v[38:39], 2, s[4:5]
	global_load_dwordx4 v[30:33], v[30:31], off nt
	s_nop 0
	global_load_dwordx4 v[34:37], v[34:35], off nt
	v_lshl_add_u64 v[40:41], v[40:41], 2, s[4:5]
	global_load_dword v94, v[38:39], off
	global_load_dword v130, v[40:41], off
	v_add_u32_e32 v54, 32, v18
	v_add_u32_e32 v56, 36, v18
	v_ashrrev_i32_e32 v55, 31, v54
	v_ashrrev_i32_e32 v57, 31, v56
	v_lshlrev_b64 v[38:39], 16, v[54:55]
	v_lshlrev_b64 v[40:41], 16, v[56:57]
	v_lshl_add_u64 v[38:39], v[16:17], 0, v[38:39]
	v_lshl_add_u64 v[44:45], v[16:17], 0, v[40:41]
	v_lshl_add_u64 v[40:41], v[42:43], 2, s[4:5]
	v_lshl_add_u64 v[46:47], v[46:47], 2, s[4:5]
	global_load_dword v132, v[40:41], off
	s_nop 0
	global_load_dwordx4 v[38:41], v[38:39], off nt
	s_nop 0
	global_load_dwordx4 v[42:45], v[44:45], off nt
	v_add_u32_e32 v58, 40, v18
	global_load_dword v134, v[46:47], off
	v_add_u32_e32 v62, 44, v18
	v_ashrrev_i32_e32 v59, 31, v58
	v_ashrrev_i32_e32 v63, 31, v62
	v_lshl_add_u64 v[48:49], v[48:49], 2, s[4:5]
	global_load_dword v136, v[48:49], off
	v_lshlrev_b64 v[46:47], 16, v[58:59]
	v_lshlrev_b64 v[48:49], 16, v[62:63]
	v_lshl_add_u64 v[46:47], v[16:17], 0, v[46:47]
	v_lshl_add_u64 v[50:51], v[16:17], 0, v[48:49]
	v_lshl_add_u64 v[54:55], v[54:55], 2, s[4:5]
	global_load_dwordx4 v[46:49], v[46:47], off nt
	s_nop 0
	global_load_dwordx4 v[50:53], v[50:51], off nt
	v_lshl_add_u64 v[56:57], v[56:57], 2, s[4:5]
	global_load_dword v138, v[54:55], off
	global_load_dword v140, v[56:57], off
	v_add_u32_e32 v64, 48, v18
	v_add_u32_e32 v142, 52, v18
	v_ashrrev_i32_e32 v65, 31, v64
	v_ashrrev_i32_e32 v143, 31, v142
	v_lshlrev_b64 v[54:55], 16, v[64:65]
	v_lshlrev_b64 v[56:57], 16, v[142:143]
	v_lshl_add_u64 v[54:55], v[16:17], 0, v[54:55]
	v_lshl_add_u64 v[60:61], v[16:17], 0, v[56:57]
	v_lshl_add_u64 v[56:57], v[58:59], 2, s[4:5]
	v_lshl_add_u64 v[62:63], v[62:63], 2, s[4:5]
	global_load_dword v144, v[56:57], off
	s_nop 0
	global_load_dwordx4 v[54:57], v[54:55], off nt
	s_nop 0
	global_load_dwordx4 v[58:61], v[60:61], off nt
	v_add_u32_e32 v146, 56, v18
	global_load_dword v148, v[62:63], off
	v_add_u32_e32 v150, 60, v18
	v_ashrrev_i32_e32 v147, 31, v146
	v_ashrrev_i32_e32 v151, 31, v150
	v_lshl_add_u64 v[18:19], v[64:65], 2, s[4:5]
	global_load_dword v152, v[18:19], off
	v_lshlrev_b64 v[62:63], 16, v[146:147]
	v_lshlrev_b64 v[18:19], 16, v[150:151]
	v_lshl_add_u64 v[62:63], v[16:17], 0, v[62:63]
	v_lshl_add_u64 v[64:65], v[16:17], 0, v[18:19]
	v_lshl_add_u64 v[142:143], v[142:143], 2, s[4:5]
	global_load_dwordx4 v[16:19], v[62:63], off nt
	s_nop 0
	global_load_dwordx4 v[62:65], v[64:65], off nt
	s_and_b32 s0, s0, 0xffffff80
	global_load_dword v142, v[142:143], off
	s_add_u32 s0, s1, s0
	s_addc_u32 s1, s14, 0
	s_waitcnt vmcnt(25)
	v_pk_mul_f32 v[12:13], v[12:13], v[66:67] op_sel_hi:[1,0]
	v_pk_mul_f32 v[14:15], v[14:15], v[66:67] op_sel_hi:[1,0]
	ds_write2_b32 v97, v12, v13 offset1:1
	ds_write2_b32 v97, v14, v15 offset0:2 offset1:3
	v_lshl_add_u64 v[12:13], v[146:147], 2, s[4:5]
	global_load_dword v12, v[12:13], off
	v_add_u32_e32 v13, v96, v99
	s_waitcnt vmcnt(23)
	v_pk_mul_f32 v[8:9], v[8:9], v[90:91] op_sel_hi:[1,0]
	ds_write2_b32 v13, v8, v9 offset1:1
	v_lshl_add_u64 v[8:9], v[150:151], 2, s[4:5]
	global_load_dword v8, v[8:9], off
	v_add_u32_e32 v9, 0x410, v13
	s_waitcnt vmcnt(23)
	v_pk_mul_f32 v[4:5], v[4:5], v[92:93] op_sel_hi:[1,0]
	v_pk_mul_f32 v[6:7], v[6:7], v[92:93] op_sel_hi:[1,0]
	ds_write2_b32 v9, v4, v5 offset1:1
	v_add_u32_e32 v4, 0x418, v13
	ds_write2_b32 v4, v6, v7 offset1:1
	v_add_u32_e32 v4, 0x820, v13
	v_pk_mul_f32 v[10:11], v[10:11], v[90:91] op_sel_hi:[1,0]
	ds_write2_b32 v13, v10, v11 offset0:2 offset1:3
	s_waitcnt vmcnt(20)
	v_pk_mul_f32 v[0:1], v[0:1], v[94:95] op_sel_hi:[1,0]
	v_pk_mul_f32 v[2:3], v[2:3], v[94:95] op_sel_hi:[1,0]
	ds_write2_b32 v4, v0, v1 offset1:1
	v_add_u32_e32 v0, 0x828, v13
	ds_write2_b32 v0, v2, v3 offset1:1
	s_waitcnt vmcnt(19)
	v_pk_mul_f32 v[2:3], v[22:23], v[130:131] op_sel_hi:[1,0]
	v_add_u32_e32 v4, 0xc30, v13
	v_pk_mul_f32 v[0:1], v[24:25], v[130:131] op_sel_hi:[1,0]
	ds_write2_b32 v4, v2, v3 offset1:1
	v_add_u32_e32 v2, 0xc38, v13
	ds_write2_b32 v2, v0, v1 offset1:1
	s_waitcnt vmcnt(18)
	v_pk_mul_f32 v[2:3], v[26:27], v[132:133] op_sel_hi:[1,0]
	v_add_u32_e32 v4, 0x1040, v13
	v_pk_mul_f32 v[0:1], v[28:29], v[132:133] op_sel_hi:[1,0]
	ds_write2_b32 v4, v2, v3 offset1:1
	v_add_u32_e32 v2, 0x1048, v13
	ds_write2_b32 v2, v0, v1 offset1:1
	s_waitcnt vmcnt(15)
	v_pk_mul_f32 v[2:3], v[30:31], v[134:135] op_sel_hi:[1,0]
	v_add_u32_e32 v4, 0x1450, v13
	ds_write2_b32 v4, v2, v3 offset1:1
	v_add_u32_e32 v4, v96, v100
	v_pk_mul_f32 v[0:1], v[32:33], v[134:135] op_sel_hi:[1,0]
	s_waitcnt vmcnt(14)
	v_pk_mul_f32 v[2:3], v[34:35], v[136:137] op_sel_hi:[1,0]
	v_add_u32_e32 v5, 0x410, v4
	ds_write2_b32 v4, v0, v1 offset0:2 offset1:3
	v_pk_mul_f32 v[0:1], v[36:37], v[136:137] op_sel_hi:[1,0]
	ds_write2_b32 v5, v2, v3 offset1:1
	v_add_u32_e32 v2, 0x418, v4
	ds_write2_b32 v2, v0, v1 offset1:1
	s_waitcnt vmcnt(11)
	v_pk_mul_f32 v[2:3], v[38:39], v[138:139] op_sel_hi:[1,0]
	v_add_u32_e32 v5, 0x820, v4
	v_pk_mul_f32 v[0:1], v[40:41], v[138:139] op_sel_hi:[1,0]
	ds_write2_b32 v5, v2, v3 offset1:1
	v_add_u32_e32 v2, 0x828, v4
	ds_write2_b32 v2, v0, v1 offset1:1
	s_waitcnt vmcnt(10)
	v_pk_mul_f32 v[2:3], v[42:43], v[140:141] op_sel_hi:[1,0]
	v_add_u32_e32 v5, 0xc30, v4
	v_pk_mul_f32 v[0:1], v[44:45], v[140:141] op_sel_hi:[1,0]
	ds_write2_b32 v5, v2, v3 offset1:1
	v_add_u32_e32 v2, 0xc38, v4
	ds_write2_b32 v2, v0, v1 offset1:1
	s_waitcnt vmcnt(9)
	v_pk_mul_f32 v[2:3], v[46:47], v[144:145] op_sel_hi:[1,0]
	v_add_u32_e32 v5, 0x1040, v4
	v_pk_mul_f32 v[0:1], v[48:49], v[144:145] op_sel_hi:[1,0]
	ds_write2_b32 v5, v2, v3 offset1:1
	v_add_u32_e32 v2, 0x1048, v4
	ds_write2_b32 v2, v0, v1 offset1:1
	s_waitcnt vmcnt(6)
	v_pk_mul_f32 v[2:3], v[50:51], v[148:149] op_sel_hi:[1,0]
	v_add_u32_e32 v5, 0x1450, v4
	v_pk_mul_f32 v[0:1], v[52:53], v[148:149] op_sel_hi:[1,0]
	ds_write2_b32 v5, v2, v3 offset1:1
	v_add_u32_e32 v2, 0x1458, v4
	ds_write2_b32 v2, v0, v1 offset1:1
	s_waitcnt vmcnt(5)
	v_pk_mul_f32 v[2:3], v[54:55], v[152:153] op_sel_hi:[1,0]
	v_add_u32_e32 v5, 0x1860, v4
	v_pk_mul_f32 v[0:1], v[56:57], v[152:153] op_sel_hi:[1,0]
	ds_write2_b32 v5, v2, v3 offset1:1
	v_add_u32_e32 v2, 0x1868, v4
	ds_write2_b32 v2, v0, v1 offset1:1
	s_waitcnt vmcnt(2)
	v_pk_mul_f32 v[2:3], v[58:59], v[142:143] op_sel_hi:[1,0]
	v_add_u32_e32 v5, 0x1c70, v4
	v_pk_mul_f32 v[0:1], v[60:61], v[142:143] op_sel_hi:[1,0]
	ds_write2_b32 v5, v2, v3 offset1:1
	v_add_u32_e32 v2, 0x1c78, v4
	ds_write2_b32 v2, v0, v1 offset1:1
	s_waitcnt vmcnt(1)
	v_pk_mul_f32 v[2:3], v[16:17], v[12:13] op_sel_hi:[1,0]
	v_add_u32_e32 v5, 0x2080, v4
	v_pk_mul_f32 v[0:1], v[18:19], v[12:13] op_sel_hi:[1,0]
	ds_write2_b32 v5, v2, v3 offset1:1
	v_add_u32_e32 v2, 0x2088, v4
	ds_write2_b32 v2, v0, v1 offset1:1
	s_waitcnt vmcnt(0)
	v_pk_mul_f32 v[2:3], v[62:63], v[8:9] op_sel_hi:[1,0]
	v_add_u32_e32 v5, 0x2490, v4
	v_pk_mul_f32 v[0:1], v[64:65], v[8:9] op_sel_hi:[1,0]
	ds_write2_b32 v5, v2, v3 offset1:1
	v_add_u32_e32 v2, 0x2498, v4
	ds_write2_b32 v2, v0, v1 offset1:1
	s_waitcnt lgkmcnt(0)
	v_lshl_add_u64 v[0:1], s[0:1], 0, v[70:71]
	v_lshl_add_u64 v[0:1], v[0:1], 0, s[16:17]
	s_movk_i32 s0, 0xffc0
	v_mov_b32_e32 v2, v102

.LBB0_30:
	s_andn2_b64 vcc, exec, s[0:1]
	s_cbranch_vccnz .LBB0_34
	s_add_i32 s1, s79, 0xffffc000
	s_and_b32 s0, s1, 0xffffffc0
	v_add_u32_e32 v0, s0, v69
	s_lshl_b32 s1, s1, 8
	s_and_b32 s14, s1, 0x3f00
	v_ashrrev_i32_e32 v1, 31, v0
	v_lshl_add_u64 v[2:3], v[78:79], 0, s[14:15]
	v_lshlrev_b64 v[0:1], 14, v[0:1]
	v_lshl_add_u64 v[0:1], v[2:3], 0, v[0:1]
	v_add_co_u32_e32 v2, vcc, 0x10000, v0
	s_and_b32 s1, s26, 0x7ffff000
	s_nop 0
	v_addc_co_u32_e32 v3, vcc, 0, v1, vcc
	global_load_dwordx4 v[4:7], v[0:1], off nt
	global_load_dwordx4 v[8:11], v[2:3], off nt
	v_add_co_u32_e32 v2, vcc, 0x20000, v0
	s_movk_i32 s14, 0xffc0
	s_nop 0
	v_addc_co_u32_e32 v3, vcc, 0, v1, vcc
	v_add_co_u32_e32 v16, vcc, 0x30000, v0
	s_nop 1
	v_addc_co_u32_e32 v17, vcc, 0, v1, vcc
	global_load_dwordx4 v[12:15], v[2:3], off nt
	s_nop 0
	global_load_dwordx4 v[16:19], v[16:17], off nt
	v_add_co_u32_e32 v2, vcc, 0x40000, v0
	s_nop 1
	v_addc_co_u32_e32 v3, vcc, 0, v1, vcc
	v_add_co_u32_e32 v24, vcc, 0x50000, v0
	s_nop 1
	v_addc_co_u32_e32 v25, vcc, 0, v1, vcc
	global_load_dwordx4 v[20:23], v[2:3], off nt
	s_nop 0
	global_load_dwordx4 v[24:27], v[24:25], off nt
	v_add_co_u32_e32 v2, vcc, 0x60000, v0
	s_nop 1
	v_addc_co_u32_e32 v3, vcc, 0, v1, vcc
	v_add_co_u32_e32 v32, vcc, 0x70000, v0
	s_nop 1
	v_addc_co_u32_e32 v33, vcc, 0, v1, vcc
	global_load_dwordx4 v[28:31], v[2:3], off nt
	s_nop 0
	global_load_dwordx4 v[32:35], v[32:33], off nt
	v_add_co_u32_e32 v2, vcc, 0x80000, v0
	s_nop 1
	v_addc_co_u32_e32 v3, vcc, 0, v1, vcc
	v_add_co_u32_e32 v40, vcc, 0x90000, v0
	s_nop 1
	v_addc_co_u32_e32 v41, vcc, 0, v1, vcc
	global_load_dwordx4 v[36:39], v[2:3], off nt
	s_nop 0
	global_load_dwordx4 v[40:43], v[40:41], off nt
	v_add_co_u32_e32 v2, vcc, 0xa0000, v0
	s_nop 1
	v_addc_co_u32_e32 v3, vcc, 0, v1, vcc
	v_add_co_u32_e32 v48, vcc, 0xb0000, v0
	s_nop 1
	v_addc_co_u32_e32 v49, vcc, 0, v1, vcc
	global_load_dwordx4 v[44:47], v[2:3], off nt
	s_nop 0
	global_load_dwordx4 v[48:51], v[48:49], off nt
	v_add_co_u32_e32 v2, vcc, 0xc0000, v0
	s_nop 1
	v_addc_co_u32_e32 v3, vcc, 0, v1, vcc
	v_add_co_u32_e32 v56, vcc, 0xd0000, v0
	s_nop 1
	v_addc_co_u32_e32 v57, vcc, 0, v1, vcc
	global_load_dwordx4 v[52:55], v[2:3], off nt
	s_nop 0
	global_load_dwordx4 v[56:59], v[56:57], off nt
	v_add_co_u32_e32 v2, vcc, 0xe0000, v0
	s_nop 1
	v_addc_co_u32_e32 v3, vcc, 0, v1, vcc
	global_load_dwordx4 v[60:63], v[2:3], off nt
	v_add_co_u32_e32 v0, vcc, 0xf0000, v0
	s_nop 1
	v_addc_co_u32_e32 v1, vcc, 0, v1, vcc
	global_load_dwordx4 v[64:67], v[0:1], off nt
	v_add_u32_e32 v0, 0x30c8, v97
	v_subrev_u32_e32 v2, s1, v101
	s_mov_b32 s1, s15
	v_mov_b32_e32 v3, v102
	s_waitcnt vmcnt(15)
	ds_write2_b32 v97, v4, v5 offset1:1
	ds_write2_b32 v97, v6, v7 offset0:2 offset1:3
	s_waitcnt vmcnt(14)
	ds_write2_b32 v104, v8, v9 offset1:1
	ds_write2_b32 v105, v10, v11 offset1:1
	s_waitcnt vmcnt(13)
	ds_write2_b32 v106, v12, v13 offset1:1
	ds_write2_b32 v107, v14, v15 offset1:1
	s_waitcnt vmcnt(12)
	ds_write2_b32 v108, v16, v17 offset1:1
	ds_write2_b32 v109, v18, v19 offset1:1
	s_waitcnt vmcnt(11)
	ds_write2_b32 v110, v20, v21 offset1:1
	ds_write2_b32 v111, v22, v23 offset1:1
	s_waitcnt vmcnt(10)
	ds_write2_b32 v112, v24, v25 offset1:1
	ds_write2_b32 v113, v26, v27 offset1:1
	s_waitcnt vmcnt(9)
	ds_write2_b32 v114, v28, v29 offset1:1
	ds_write2_b32 v115, v30, v31 offset1:1
	s_waitcnt vmcnt(8)
	ds_write2_b32 v116, v32, v33 offset1:1
	ds_write2_b32 v117, v34, v35 offset1:1
	s_waitcnt vmcnt(7)
	ds_write2_b32 v118, v36, v37 offset1:1
	ds_write2_b32 v119, v38, v39 offset1:1
	s_waitcnt vmcnt(6)
	ds_write2_b32 v120, v40, v41 offset1:1
	ds_write2_b32 v123, v42, v43 offset1:1
	s_waitcnt vmcnt(5)
	ds_write2_b32 v124, v44, v45 offset1:1
	ds_write2_b32 v125, v46, v47 offset1:1
	s_waitcnt vmcnt(4)
	ds_write2_b32 v126, v48, v49 offset1:1
	ds_write2_b32 v127, v50, v51 offset1:1
	s_waitcnt vmcnt(3)
	ds_write2_b32 v128, v52, v53 offset1:1
	ds_write2_b32 v0, v54, v55 offset1:1
	v_add_u32_e32 v0, 0x34d0, v97
	s_waitcnt vmcnt(2)
	ds_write2_b32 v0, v56, v57 offset1:1
	v_add_u32_e32 v0, 0x34d8, v97
	ds_write2_b32 v0, v58, v59 offset1:1
	v_add_u32_e32 v0, 0x38e0, v97
	s_waitcnt vmcnt(1)
	ds_write2_b32 v0, v60, v61 offset1:1
	v_add_u32_e32 v0, 0x38e8, v97
	ds_write2_b32 v0, v62, v63 offset1:1
	v_add_u32_e32 v0, 0x3cf0, v97
	s_waitcnt vmcnt(0)
	ds_write2_b32 v0, v64, v65 offset1:1
	v_add_u32_e32 v0, 0x3cf8, v97
	ds_write2_b32 v0, v66, v67 offset1:1
	s_waitcnt lgkmcnt(0)
	v_lshl_add_u64 v[0:1], s[0:1], 1, v[80:81]

.LBB0_35:
	s_andn2_b64 vcc, exec, s[0:1]
	s_cbranch_vccnz .LBB0_12
	s_ashr_i32 s0, s79, 31
	s_lshr_b32 s0, s0, 24
	s_add_i32 s0, s79, s0
	s_ashr_i32 s0, s0, 8
	s_lshl_b32 s18, s0, 6
	s_lshl_b32 s14, s0, 14
	s_lshl_b32 s0, s79, 6
	s_sub_i32 s0, s0, s14
	v_add_u32_e32 v64, s18, v69
	s_ashr_i32 s1, s0, 31
	v_ashrrev_i32_e32 v65, 31, v64
	v_lshl_add_u64 v[0:1], s[0:1], 2, v[82:83]
	v_lshlrev_b64 v[2:3], 16, v[64:65]
	v_lshl_add_u64 v[0:1], v[0:1], 0, v[2:3]
	v_add_co_u32_e32 v2, vcc, s30, v0
	s_nop 1
	v_addc_co_u32_e32 v3, vcc, 0, v1, vcc
	global_load_dwordx4 v[56:59], v[0:1], off nt
	global_load_dwordx4 v[60:63], v[2:3], off nt
	v_add_co_u32_e32 v2, vcc, s36, v0
	s_nop 1
	v_addc_co_u32_e32 v3, vcc, 0, v1, vcc
	v_add_co_u32_e32 v4, vcc, s37, v0
	s_nop 1
	v_addc_co_u32_e32 v5, vcc, 0, v1, vcc
	global_load_dwordx4 v[48:51], v[2:3], off nt
	global_load_dwordx4 v[52:55], v[4:5], off nt
	v_add_co_u32_e32 v2, vcc, s68, v0
	s_nop 1
	v_addc_co_u32_e32 v3, vcc, 0, v1, vcc
	v_add_co_u32_e32 v4, vcc, s69, v0
	s_nop 1
	v_addc_co_u32_e32 v5, vcc, 0, v1, vcc
	global_load_dwordx4 v[40:43], v[2:3], off nt
	global_load_dwordx4 v[44:47], v[4:5], off nt
	v_add_co_u32_e32 v2, vcc, s70, v0
	s_nop 1
	v_addc_co_u32_e32 v3, vcc, 0, v1, vcc
	v_add_co_u32_e32 v4, vcc, s71, v0
	s_nop 1
	v_addc_co_u32_e32 v5, vcc, 0, v1, vcc
	global_load_dwordx4 v[32:35], v[2:3], off nt
	global_load_dwordx4 v[36:39], v[4:5], off nt
	v_add_co_u32_e32 v2, vcc, s72, v0
	s_nop 1
	v_addc_co_u32_e32 v3, vcc, 0, v1, vcc
	v_add_co_u32_e32 v4, vcc, s73, v0
	s_nop 1
	v_addc_co_u32_e32 v5, vcc, 0, v1, vcc
	global_load_dwordx4 v[24:27], v[2:3], off nt
	global_load_dwordx4 v[28:31], v[4:5], off nt
	v_add_co_u32_e32 v2, vcc, s74, v0
	s_nop 1
	v_addc_co_u32_e32 v3, vcc, 0, v1, vcc
	v_add_co_u32_e32 v4, vcc, s75, v0
	s_nop 1
	v_addc_co_u32_e32 v5, vcc, 0, v1, vcc
	v_add_co_u32_e32 v6, vcc, s78, v0
	s_nop 1
	v_addc_co_u32_e32 v7, vcc, 0, v1, vcc
	v_add_co_u32_e32 v12, vcc, 0x340000, v0
	s_nop 1
	v_addc_co_u32_e32 v13, vcc, 0, v1, vcc
	v_add_co_u32_e32 v66, vcc, 0x380000, v0
	s_nop 1
	v_addc_co_u32_e32 v67, vcc, 0, v1, vcc
	v_add_co_u32_e32 v90, vcc, 0x3c0000, v0
	s_nop 1
	v_addc_co_u32_e32 v91, vcc, 0, v1, vcc
	global_load_dwordx4 v[16:19], v[2:3], off nt
	global_load_dwordx4 v[20:23], v[4:5], off nt
	global_load_dwordx4 v[8:11], v[6:7], off nt
	s_nop 0
	global_load_dwordx4 v[12:15], v[12:13], off nt
	s_nop 0
	global_load_dwordx4 v[0:3], v[66:67], off nt
	global_load_dwordx4 v[4:7], v[90:91], off nt
	v_cndmask_b32_e64 v66, 0, 1, s[6:7]
	v_cmp_ne_u32_e64 s[0:1], 1, v66
	s_andn2_b64 vcc, exec, s[6:7]
	v_lshl_add_u64 v[90:91], v[64:65], 2, s[42:43]
	s_cbranch_vccnz .LBB0_63
	global_load_dword v64, v[90:91], off
	global_load_dword v130, v[90:91], off offset:16
	s_waitcnt vmcnt(1)
	v_pk_mul_f32 v[92:93], v[58:59], v[64:65] op_sel_hi:[1,0]
	v_pk_mul_f32 v[94:95], v[56:57], v[64:65] op_sel_hi:[1,0]
	s_waitcnt vmcnt(0)
	v_pk_mul_f32 v[66:67], v[62:63], v[130:131] op_sel_hi:[1,0]
	v_pk_mul_f32 v[64:65], v[60:61], v[130:131] op_sel_hi:[1,0]
	s_cbranch_execnz .LBB0_39

.LBB0_74:
	v_ashrrev_i32_e32 v34, 10, v36
	v_ashrrev_i32_e32 v35, 31, v34
	v_and_b32_e32 v42, 0x1ff8, v37
	v_lshlrev_b64 v[24:25], 16, v[34:35]
	v_lshl_add_u64 v[24:25], s[56:57], 0, v[24:25]
	v_lshlrev_b32_e32 v32, 2, v42
	v_lshl_add_u64 v[28:29], v[24:25], 0, v[32:33]
	global_load_dwordx4 v[24:27], v[28:29], off offset:16 nt
	s_nop 0
	global_load_dwordx4 v[28:31], v[28:29], off nt
	v_add_u32_e32 v40, s3, v36
	v_cmp_gt_i32_e64 s[6:7], s11, v40
	s_and_saveexec_b64 s[0:1], s[6:7]
	s_cbranch_execz .LBB0_76
	v_ashrrev_i32_e32 v0, 10, v40
	v_add_u32_e32 v1, s24, v38
	v_and_b32_e32 v2, 0x1ff8, v1
	v_ashrrev_i32_e32 v1, 31, v0
	v_lshlrev_b64 v[0:1], 16, v[0:1]
	v_lshl_add_u64 v[0:1], s[56:57], 0, v[0:1]
	v_lshlrev_b32_e32 v2, 2, v2
	v_mov_b32_e32 v3, v33
	v_lshl_add_u64 v[12:13], v[0:1], 0, v[2:3]
	global_load_dwordx4 v[0:3], v[12:13], off nt
	s_nop 0
	global_load_dwordx4 v[12:15], v[12:13], off offset:16 nt
.LBB0_76:
	s_or_b64 exec, exec, s[0:1]
	v_add_u32_e32 v41, s21, v36
	v_cmp_gt_i32_e64 s[4:5], s11, v41
	s_and_saveexec_b64 s[0:1], s[4:5]
	s_cbranch_execz .LBB0_78
	v_ashrrev_i32_e32 v4, 10, v41
	v_ashrrev_i32_e32 v5, 31, v4
	v_lshlrev_b64 v[4:5], 16, v[4:5]
	v_lshl_add_u64 v[4:5], s[56:57], 0, v[4:5]
	v_lshl_add_u64 v[4:5], v[4:5], 0, v[32:33]
	global_load_dwordx4 v[8:11], v[4:5], off nt
	s_nop 0
	global_load_dwordx4 v[4:7], v[4:5], off offset:16 nt
.LBB0_78:
	s_or_b64 exec, exec, s[0:1]
	v_add_u32_e32 v39, s22, v36
	v_cmp_gt_i32_e64 s[0:1], s11, v39
	s_and_saveexec_b64 s[18:19], s[0:1]
	s_cbranch_execz .LBB0_80
	v_ashrrev_i32_e32 v16, 10, v39
	v_add_u32_e32 v17, s23, v38
	v_and_b32_e32 v18, 0x1ff8, v17
	v_ashrrev_i32_e32 v17, 31, v16
	v_lshlrev_b64 v[16:17], 16, v[16:17]
	v_lshl_add_u64 v[16:17], s[56:57], 0, v[16:17]
	v_lshlrev_b32_e32 v32, 2, v18
	v_lshl_add_u64 v[16:17], v[16:17], 0, v[32:33]
	global_load_dwordx4 v[20:23], v[16:17], off nt
	s_nop 0
	global_load_dwordx4 v[16:19], v[16:17], off offset:16 nt

.LBB0_89:
	v_add_co_u32_e32 v0, vcc, 0xffffd000, v34
	s_nop 1
	v_addc_co_u32_e32 v1, vcc, -1, v35, vcc
	global_load_dwordx4 v[46:49], v[0:1], off offset:-3072 nt
	global_load_dwordx4 v[50:53], v[0:1], off offset:-2048 nt
	global_load_dwordx4 v[54:57], v[0:1], off offset:-1024 nt
	global_load_dwordx4 v[58:61], v[0:1], off nt
	v_add_co_u32_e32 v0, vcc, 0xffffe000, v34
	s_waitcnt vmcnt(2)
	v_cvt_pk_bf16_f32 v82, v50, v51
	s_nop 0
	v_addc_co_u32_e32 v1, vcc, -1, v35, vcc
	global_load_dwordx4 v[62:65], v[0:1], off offset:-3072 nt
	global_load_dwordx4 v[66:69], v[0:1], off offset:-2048 nt
	global_load_dwordx4 v[70:73], v[0:1], off offset:-1024 nt
	global_load_dwordx4 v[74:77], v[0:1], off nt
	global_load_dwordx4 v[12:15], v[34:35], off offset:-3072 nt
	s_waitcnt lgkmcnt(0)
	global_load_dwordx4 v[4:7], v[34:35], off offset:-2048 nt
	v_add_co_u32_e32 v78, vcc, 0xfffff000, v34
	v_mul_f32_e32 v45, v47, v47
	s_nop 0
	v_addc_co_u32_e32 v79, vcc, -1, v35, vcc
	global_load_dwordx4 v[16:19], v[78:79], off offset:-3072 nt
	global_load_dwordx4 v[8:11], v[34:35], off offset:-1024 nt
	global_load_dwordx4 v[0:3], v[34:35], off nt
	global_load_dwordx4 v[28:31], v[78:79], off offset:-2048 nt
	global_load_dwordx4 v[24:27], v[78:79], off offset:-1024 nt
	global_load_dwordx4 v[20:23], v[34:35], off offset:-4096 nt
	v_mul_f32_e32 v88, v49, v49
	v_mul_f32_e32 v89, v51, v51
	v_mul_f32_e32 v90, v53, v53
	v_cvt_pk_bf16_f32 v83, v52, v53
	s_waitcnt vmcnt(13)
	v_mul_f32_e32 v51, v55, v55
	v_mul_f32_e32 v53, v57, v57
	v_fmac_f32_e32 v45, v46, v46
	v_fmac_f32_e32 v88, v48, v48
	v_fmac_f32_e32 v89, v50, v50
	v_fmac_f32_e32 v90, v52, v52
	v_cvt_pk_bf16_f32 v84, v54, v55
	v_cvt_pk_bf16_f32 v85, v56, v57
	s_waitcnt vmcnt(12)
	v_mul_f32_e32 v55, v59, v59
	v_mul_f32_e32 v57, v61, v61
	v_cvt_pk_bf16_f32 v86, v58, v59
	v_fmac_f32_e32 v51, v54, v54
	v_fmac_f32_e32 v53, v56, v56
	v_add_f32_e32 v45, v45, v88
	v_add_f32_e32 v59, v89, v90
	v_add_co_u32_e32 v80, vcc, s3, v32
	v_fmac_f32_e32 v55, v58, v58
	v_fmac_f32_e32 v57, v60, v60
	v_add_f32_e32 v51, v51, v53
	v_add_f32_e32 v45, v45, v59
	v_addc_co_u32_e32 v81, vcc, -1, v33, vcc
	v_cvt_pk_bf16_f32 v78, v46, v47
	s_waitcnt vmcnt(11)
	v_cvt_pk_bf16_f32 v46, v62, v63
	v_mul_f32_e32 v50, v63, v63
	v_mul_f32_e32 v52, v65, v65
	v_add_f32_e32 v53, v55, v57
	v_fmac_f32_e32 v50, v62, v62
	v_fmac_f32_e32 v52, v64, v64
	v_add_f32_e32 v45, v45, v51
	v_cvt_pk_bf16_f32 v47, v64, v65
	s_waitcnt vmcnt(10)
	v_mul_f32_e32 v54, v67, v67
	v_mul_f32_e32 v56, v69, v69
	global_store_dwordx2 v[80:81], v[46:47], off offset:-1536
	v_add_f32_e32 v46, v50, v52
	v_add_f32_e32 v45, v45, v53
	s_waitcnt vmcnt(10)
	v_mul_f32_e32 v58, v71, v71
	v_fmac_f32_e32 v54, v66, v66
	v_fmac_f32_e32 v56, v68, v68
	v_add_f32_e32 v45, v45, v46
	v_mul_f32_e32 v46, v73, v73
	v_fmac_f32_e32 v58, v70, v70
	v_add_f32_e32 v47, v54, v56
	v_fmac_f32_e32 v46, v72, v72
	v_add_f32_e32 v45, v45, v47
	v_add_f32_e32 v46, v58, v46
	v_add_f32_e32 v45, v45, v46
	v_cvt_pk_bf16_f32 v46, v70, v71
	v_cvt_pk_bf16_f32 v47, v72, v73
	global_store_dwordx2 v[80:81], v[46:47], off offset:-512
	s_waitcnt vmcnt(10)
	v_mul_f32_e32 v46, v75, v75
	v_mul_f32_e32 v47, v77, v77
	v_fmac_f32_e32 v46, v74, v74
	v_fmac_f32_e32 v47, v76, v76
	v_add_f32_e32 v46, v46, v47
	v_add_f32_e32 v45, v45, v46
	v_cvt_pk_bf16_f32 v46, v74, v75
	v_cvt_pk_bf16_f32 v47, v76, v77
	global_store_dwordx2 v[32:33], v[46:47], off offset:-4096
	s_waitcnt vmcnt(8)
	v_mul_f32_e32 v46, v17, v17
	v_mul_f32_e32 v47, v19, v19
	v_fmac_f32_e32 v46, v16, v16
	v_fmac_f32_e32 v47, v18, v18
	v_add_f32_e32 v46, v46, v47
	v_add_f32_e32 v45, v45, v46
	s_waitcnt vmcnt(5)
	v_mul_f32_e32 v46, v29, v29
	v_mul_f32_e32 v47, v31, v31
	v_fmac_f32_e32 v46, v28, v28
	v_fmac_f32_e32 v47, v30, v30
	v_add_f32_e32 v46, v46, v47
	v_add_f32_e32 v45, v45, v46
	s_waitcnt vmcnt(4)
	v_mul_f32_e32 v46, v25, v25
	v_mul_f32_e32 v47, v27, v27
	v_fmac_f32_e32 v46, v24, v24
	v_fmac_f32_e32 v47, v26, v26
	v_add_f32_e32 v46, v46, v47
	v_add_f32_e32 v45, v45, v46
	s_waitcnt vmcnt(3)
	v_mul_f32_e32 v46, v21, v21
	v_mul_f32_e32 v47, v23, v23
	v_fmac_f32_e32 v46, v20, v20
	v_fmac_f32_e32 v47, v22, v22
	v_add_f32_e32 v46, v46, v47
	v_add_f32_e32 v45, v45, v46
	v_mul_f32_e32 v46, v13, v13
	v_mul_f32_e32 v47, v15, v15
	v_fmac_f32_e32 v46, v12, v12
	v_fmac_f32_e32 v47, v14, v14
	v_add_f32_e32 v46, v46, v47
	v_add_f32_e32 v45, v45, v46
	v_mul_f32_e32 v46, v5, v5
	v_mul_f32_e32 v47, v7, v7
	v_fmac_f32_e32 v46, v4, v4
	v_fmac_f32_e32 v47, v6, v6
	v_add_f32_e32 v46, v46, v47
	v_add_f32_e32 v45, v45, v46
	v_mul_f32_e32 v46, v9, v9
	v_mul_f32_e32 v47, v11, v11
	v_fmac_f32_e32 v46, v8, v8
	v_fmac_f32_e32 v47, v10, v10
	v_add_f32_e32 v46, v46, v47
	v_add_f32_e32 v45, v45, v46
	v_mul_f32_e32 v46, v1, v1
	v_mul_f32_e32 v47, v3, v3
	v_fmac_f32_e32 v46, v0, v0
	v_fmac_f32_e32 v47, v2, v2
	v_add_f32_e32 v46, v46, v47
	v_cmp_lt_i32_e32 vcc, v38, v37
	v_add_f32_e32 v45, v45, v46
	v_cvt_pk_bf16_f32 v16, v16, v17
	v_cvt_pk_bf16_f32 v17, v18, v19
	global_store_dwordx2 v[32:33], v[16:17], off offset:-3584
	v_cndmask_b32_e32 v46, v36, v38, vcc
	v_lshlrev_b32_e32 v46, 2, v46
	ds_bpermute_b32 v46, v46, v45
	v_cmp_lt_i32_e32 vcc, v39, v37
	v_cvt_pk_bf16_f32 v16, v28, v29
	v_cvt_pk_bf16_f32 v12, v12, v13
	v_cvt_pk_bf16_f32 v4, v4, v5
	s_waitcnt lgkmcnt(0)
	v_add_f32_e32 v18, v45, v46
	v_cvt_pk_bf16_f32 v13, v14, v15
	v_cndmask_b32_e32 v17, v36, v39, vcc
	v_lshlrev_b32_e32 v17, 2, v17
	ds_bpermute_b32 v19, v17, v18
	v_cmp_lt_i32_e32 vcc, v40, v37
	v_cvt_pk_bf16_f32 v17, v30, v31
	global_store_dwordx2 v[32:33], v[16:17], off offset:-3072
	v_cvt_pk_bf16_f32 v17, v26, v27
	s_waitcnt lgkmcnt(0)
	v_add_f32_e32 v18, v18, v19
	v_cndmask_b32_e32 v19, v36, v40, vcc
	v_lshlrev_b32_e32 v19, 2, v19
	ds_bpermute_b32 v19, v19, v18
	v_cvt_pk_bf16_f32 v16, v24, v25
	global_store_dwordx2 v[32:33], v[16:17], off offset:-2560
	v_cvt_pk_bf16_f32 v17, v22, v23
	v_cmp_lt_i32_e32 vcc, v41, v37
	v_cvt_pk_bf16_f32 v16, v20, v21
	global_store_dwordx2 v[32:33], v[16:17], off offset:-2048
	s_waitcnt lgkmcnt(0)
	v_add_f32_e32 v16, v18, v19
	v_cndmask_b32_e32 v17, v36, v41, vcc
	v_lshlrev_b32_e32 v17, 2, v17
	ds_bpermute_b32 v17, v17, v16
	v_cmp_lt_i32_e32 vcc, v42, v37
	global_store_dwordx2 v[32:33], v[12:13], off offset:-1536
	v_cvt_pk_bf16_f32 v79, v48, v49
	v_cvt_pk_bf16_f32 v87, v60, v61
	s_waitcnt lgkmcnt(0)
	v_add_f32_e32 v12, v16, v17
	v_cndmask_b32_e32 v5, v36, v42, vcc
	v_lshlrev_b32_e32 v5, 2, v5
	ds_bpermute_b32 v13, v5, v12
	v_cvt_pk_bf16_f32 v5, v6, v7
	v_cmp_lt_i32_e32 vcc, v43, v37
	global_store_dwordx2 v[32:33], v[4:5], off offset:-1024
	global_store_dwordx2 v[80:81], v[78:79], off offset:-3584
	v_cndmask_b32_e32 v5, v36, v43, vcc
	s_waitcnt lgkmcnt(0)
	v_add_f32_e32 v4, v12, v13
	v_lshlrev_b32_e32 v5, 2, v5
	ds_bpermute_b32 v5, v5, v4
	global_store_dwordx2 v[80:81], v[82:83], off offset:-3072
	global_store_dwordx2 v[80:81], v[84:85], off offset:-2560
	global_store_dwordx2 v[80:81], v[86:87], off offset:-2048
	v_cvt_pk_bf16_f32 v48, v66, v67
	v_cvt_pk_bf16_f32 v49, v68, v69
	global_store_dwordx2 v[80:81], v[48:49], off offset:-1024
	v_cvt_pk_bf16_f32 v6, v8, v9
	v_cvt_pk_bf16_f32 v7, v10, v11
	global_store_dwordx2 v[32:33], v[6:7], off offset:-512
	v_cvt_pk_bf16_f32 v0, v0, v1
	v_cvt_pk_bf16_f32 v1, v2, v3
	global_store_dwordx2 v[32:33], v[0:1], off
	s_and_saveexec_b64 s[18:19], s[0:1]
	s_cbranch_execz .LBB0_88
	s_waitcnt lgkmcnt(0)
	v_add_f32_e32 v0, v4, v5
	global_store_dword v44, v0, s[4:5]
	s_branch .LBB0_88

.LBB0_434:
	v_lshl_add_u32 v196, s20, 8, v204
	v_lshl_add_u32 v192, s22, 8, v206
	v_ashrrev_i32_e32 v193, 31, v192
	v_ashrrev_i32_e32 v197, 31, v196
	v_lshl_add_u64 v[194:195], v[192:193], 2, s[40:41]
	v_lshlrev_b64 v[128:129], 14, v[196:197]
	v_lshl_add_u64 v[128:129], v[194:195], 0, v[128:129]
	global_load_dwordx4 v[212:215], v[128:129], off nt
	global_load_dwordx4 v[216:219], v[128:129], off offset:16 nt
	global_load_dwordx4 v[220:223], v[128:129], off offset:512 nt
	global_load_dwordx4 v[224:227], v[128:129], off offset:528 nt
	v_or_b32_e32 v202, 16, v196
	v_or_b32_e32 v200, 32, v196
	v_or_b32_e32 v198, 48, v196
	v_ashrrev_i32_e32 v203, 31, v202
	v_ashrrev_i32_e32 v201, 31, v200
	v_ashrrev_i32_e32 v199, 31, v198
	v_lshlrev_b64 v[128:129], 14, v[202:203]
	v_lshlrev_b64 v[130:131], 14, v[200:201]
	v_lshlrev_b64 v[132:133], 14, v[198:199]
	v_lshl_add_u64 v[128:129], v[194:195], 0, v[128:129]
	v_lshl_add_u64 v[130:131], v[194:195], 0, v[130:131]
	v_lshl_add_u64 v[132:133], v[194:195], 0, v[132:133]
	global_load_dwordx4 v[168:171], v[128:129], off offset:16 nt
	global_load_dwordx4 v[172:175], v[128:129], off nt
	global_load_dwordx4 v[160:163], v[128:129], off offset:528 nt
	global_load_dwordx4 v[164:167], v[128:129], off offset:512 nt
	global_load_dwordx4 v[152:155], v[130:131], off offset:16 nt
	global_load_dwordx4 v[156:159], v[130:131], off nt
	global_load_dwordx4 v[144:147], v[130:131], off offset:528 nt
	global_load_dwordx4 v[148:151], v[130:131], off offset:512 nt
	global_load_dwordx4 v[136:139], v[132:133], off offset:16 nt
	global_load_dwordx4 v[140:143], v[132:133], off nt
	s_nop 0
	global_load_dwordx4 v[128:131], v[132:133], off offset:528 nt
	s_nop 0
	global_load_dwordx4 v[132:135], v[132:133], off offset:512 nt
	v_and_b32_e32 v228, 64, v210
	v_xor_b32_e32 v211, 16, v210
	v_add_u32_e32 v231, 64, v228
	v_cmp_lt_i32_e32 vcc, v211, v231
	v_xor_b32_e32 v230, 32, v210
	v_lshlrev_b64 v[228:229], 13, v[196:197]
	v_cndmask_b32_e32 v211, v210, v211, vcc
	v_lshlrev_b32_e32 v211, 2, v211
	v_cmp_lt_i32_e32 vcc, v230, v231
	v_lshl_add_u64 v[228:229], s[42:43], 0, v[228:229]
	v_lshl_add_u64 v[228:229], v[192:193], 1, v[228:229]
	v_cndmask_b32_e32 v230, v210, v230, vcc
	s_waitcnt vmcnt(0)
	v_pk_add_f32 v[126:127], v[126:127], v[214:215]
	v_pk_add_f32 v[124:125], v[124:125], v[212:213]
	v_pk_add_f32 v[118:119], v[118:119], v[222:223]
	v_pk_add_f32 v[116:117], v[116:117], v[220:221]
	v_pk_add_f32 v[120:121], v[120:121], v[216:217]
	v_pk_add_f32 v[212:213], v[114:115], v[226:227]
	v_pk_add_f32 v[214:215], v[112:113], v[224:225]
	v_mul_f32_e32 v114, v125, v125
	v_mul_f32_e32 v115, v127, v127
	v_cvt_pk_bf16_f32 v112, v124, v125
	v_cvt_pk_bf16_f32 v113, v126, v127
	v_mul_f32_e32 v125, v117, v117
	v_mul_f32_e32 v127, v119, v119
	v_pk_add_f32 v[122:123], v[122:123], v[218:219]
	v_mul_f32_e32 v216, v121, v121
	v_mul_f32_e32 v218, v215, v215
	v_fmac_f32_e32 v114, v124, v124
	v_fmac_f32_e32 v115, v126, v126
	v_fmac_f32_e32 v125, v116, v116
	v_fmac_f32_e32 v127, v118, v118
	v_mul_f32_e32 v217, v123, v123
	v_mul_f32_e32 v219, v213, v213
	v_fmac_f32_e32 v216, v120, v120
	v_fmac_f32_e32 v218, v214, v214
	v_add_f32_e32 v114, v114, v115
	v_add_f32_e32 v115, v125, v127
	v_fmac_f32_e32 v217, v122, v122
	v_fmac_f32_e32 v219, v212, v212
	v_add_f32_e32 v114, v114, v216
	v_add_f32_e32 v115, v115, v218
	v_add_f32_e32 v114, v217, v114
	v_add_f32_e32 v115, v219, v115
	v_add_f32_e32 v124, v114, v115
	ds_bpermute_b32 v125, v211, v124
	v_cvt_pk_bf16_f32 v114, v120, v121
	v_cvt_pk_bf16_f32 v115, v122, v123
	global_store_dwordx4 v[228:229], v[112:115], off
	v_lshlrev_b32_e32 v120, 2, v230
	s_waitcnt lgkmcnt(0)
	v_add_f32_e32 v112, v124, v125
	ds_bpermute_b32 v113, v120, v112
	v_cvt_pk_bf16_f32 v114, v116, v117
	v_cvt_pk_bf16_f32 v115, v118, v119
	v_cvt_pk_bf16_f32 v116, v214, v215
	v_cvt_pk_bf16_f32 v117, v212, v213
	global_store_dwordx4 v[228:229], v[114:117], off offset:256
	s_and_saveexec_b64 s[20:21], s[0:1]
	s_cbranch_execz .LBB0_436
	v_lshl_add_u64 v[114:115], v[196:197], 2, s[24:25]
	s_waitcnt lgkmcnt(0)
	v_add_f32_e32 v112, v112, v113
	global_atomic_add_f32 v[114:115], v112, off

.LBB0_442:
	s_or_b64 exec, exec, s[20:21]
	v_add_u32_e32 v118, 0x80, v196
	v_ashrrev_i32_e32 v119, 31, v118
	s_waitcnt lgkmcnt(0)
	v_lshlrev_b64 v[64:65], 14, v[118:119]
	v_lshl_add_u64 v[64:65], v[194:195], 0, v[64:65]
	global_load_dwordx4 v[122:125], v[64:65], off nt
	global_load_dwordx4 v[126:129], v[64:65], off offset:16 nt
	global_load_dwordx4 v[130:133], v[64:65], off offset:512 nt
	global_load_dwordx4 v[134:137], v[64:65], off offset:528 nt
	v_add_u32_e32 v116, 0x90, v196
	v_add_u32_e32 v114, 0xa0, v196
	v_add_u32_e32 v112, 0xb0, v196
	v_ashrrev_i32_e32 v117, 31, v116
	v_ashrrev_i32_e32 v115, 31, v114
	v_ashrrev_i32_e32 v113, 31, v112
	v_lshlrev_b64 v[64:65], 14, v[116:117]
	v_lshlrev_b64 v[66:67], 14, v[114:115]
	v_lshlrev_b64 v[68:69], 14, v[112:113]
	v_lshl_add_u64 v[64:65], v[194:195], 0, v[64:65]
	v_lshl_add_u64 v[66:67], v[194:195], 0, v[66:67]
	v_lshl_add_u64 v[68:69], v[194:195], 0, v[68:69]
	global_load_dwordx4 v[104:107], v[64:65], off offset:16 nt
	global_load_dwordx4 v[108:111], v[64:65], off nt
	global_load_dwordx4 v[96:99], v[64:65], off offset:528 nt
	global_load_dwordx4 v[100:103], v[64:65], off offset:512 nt
	global_load_dwordx4 v[88:91], v[66:67], off offset:16 nt
	global_load_dwordx4 v[92:95], v[66:67], off nt
	global_load_dwordx4 v[80:83], v[66:67], off offset:528 nt
	global_load_dwordx4 v[84:87], v[66:67], off offset:512 nt
	global_load_dwordx4 v[72:75], v[68:69], off offset:16 nt
	global_load_dwordx4 v[76:79], v[68:69], off nt
	s_nop 0
	global_load_dwordx4 v[64:67], v[68:69], off offset:528 nt
	s_nop 0
	global_load_dwordx4 v[68:71], v[68:69], off offset:512 nt
	v_lshlrev_b64 v[138:139], 13, v[118:119]
	s_waitcnt vmcnt(15)
	v_pk_add_f32 v[62:63], v[62:63], v[124:125]
	v_pk_add_f32 v[60:61], v[60:61], v[122:123]
	s_waitcnt vmcnt(14)
	v_pk_add_f32 v[58:59], v[58:59], v[128:129]
	v_pk_add_f32 v[56:57], v[56:57], v[126:127]
	s_waitcnt vmcnt(13)
	v_pk_add_f32 v[54:55], v[54:55], v[132:133]
	v_pk_add_f32 v[52:53], v[52:53], v[130:131]
	s_waitcnt vmcnt(12)
	v_pk_add_f32 v[122:123], v[50:51], v[136:137]
	v_pk_add_f32 v[124:125], v[48:49], v[134:135]
	v_mul_f32_e32 v121, v61, v61
	v_mul_f32_e32 v126, v63, v63
	v_mul_f32_e32 v127, v57, v57
	v_mul_f32_e32 v128, v59, v59
	v_cvt_pk_bf16_f32 v48, v60, v61
	v_cvt_pk_bf16_f32 v49, v62, v63
	v_cvt_pk_bf16_f32 v50, v56, v57
	v_cvt_pk_bf16_f32 v51, v58, v59
	v_mul_f32_e32 v57, v53, v53
	v_mul_f32_e32 v59, v55, v55
	v_mul_f32_e32 v61, v125, v125
	v_fmac_f32_e32 v121, v60, v60
	v_fmac_f32_e32 v126, v62, v62
	v_fmac_f32_e32 v57, v52, v52
	v_fmac_f32_e32 v59, v54, v54
	v_mul_f32_e32 v63, v123, v123
	v_fmac_f32_e32 v127, v56, v56
	v_fmac_f32_e32 v61, v124, v124
	v_add_f32_e32 v56, v121, v126
	v_add_f32_e32 v57, v57, v59
	v_fmac_f32_e32 v128, v58, v58
	v_fmac_f32_e32 v63, v122, v122
	v_add_f32_e32 v56, v56, v127
	v_add_f32_e32 v57, v57, v61
	v_add_f32_e32 v56, v128, v56
	v_add_f32_e32 v57, v63, v57
	v_add_f32_e32 v58, v56, v57
	ds_bpermute_b32 v59, v211, v58
	v_lshl_add_u64 v[56:57], s[42:43], 0, v[138:139]
	v_lshl_add_u64 v[56:57], v[192:193], 1, v[56:57]
	global_store_dwordx4 v[56:57], v[48:51], off
	s_waitcnt lgkmcnt(0)
	s_nop 0
	v_add_f32_e32 v48, v58, v59
	ds_bpermute_b32 v49, v120, v48
	v_cvt_pk_bf16_f32 v50, v52, v53
	v_cvt_pk_bf16_f32 v51, v54, v55
	v_cvt_pk_bf16_f32 v52, v124, v125
	v_cvt_pk_bf16_f32 v53, v122, v123
	global_store_dwordx4 v[56:57], v[50:53], off offset:256
	s_and_saveexec_b64 s[20:21], s[0:1]
	s_cbranch_execz .LBB0_444
	v_lshl_add_u64 v[50:51], v[118:119], 2, s[24:25]
	s_waitcnt lgkmcnt(0)
	v_add_f32_e32 v48, v48, v49
	global_atomic_add_f32 v[50:51], v48, off

.LBB0_818:
	v_lshl_add_u32 v222, s38, 8, v238
	v_lshl_add_u32 v220, s40, 8, v240
	v_ashrrev_i32_e32 v221, 31, v220
	v_ashrrev_i32_e32 v223, 31, v222
	v_lshl_add_u64 v[56:57], v[220:221], 1, s[42:43]
	v_lshlrev_b64 v[58:59], 13, v[222:223]
	v_lshl_add_u64 v[58:59], v[56:57], 0, v[58:59]
	global_load_dwordx4 v[204:207], v[58:59], off nt
	global_load_dwordx4 v[200:203], v[58:59], off offset:256 nt
	v_or_b32_e32 v224, 16, v222
	v_ashrrev_i32_e32 v225, 31, v224
	v_lshlrev_b64 v[58:59], 13, v[224:225]
	v_or_b32_e32 v226, 32, v222
	v_lshl_add_u64 v[58:59], v[56:57], 0, v[58:59]
	v_ashrrev_i32_e32 v227, 31, v226
	global_load_dwordx4 v[196:199], v[58:59], off nt
	global_load_dwordx4 v[192:195], v[58:59], off offset:256 nt
	v_lshlrev_b64 v[58:59], 13, v[226:227]
	v_or_b32_e32 v228, 48, v222
	v_lshl_add_u64 v[58:59], v[56:57], 0, v[58:59]
	v_ashrrev_i32_e32 v229, 31, v228
	global_load_dwordx4 v[188:191], v[58:59], off nt
	global_load_dwordx4 v[184:187], v[58:59], off offset:256 nt
	v_lshlrev_b64 v[58:59], 13, v[228:229]
	v_add_u32_e32 v230, 0x80, v222
	v_lshl_add_u64 v[58:59], v[56:57], 0, v[58:59]
	v_ashrrev_i32_e32 v231, 31, v230
	global_load_dwordx4 v[180:183], v[58:59], off nt
	global_load_dwordx4 v[176:179], v[58:59], off offset:256 nt
	v_lshlrev_b64 v[58:59], 13, v[230:231]
	v_add_u32_e32 v232, 0x90, v222
	v_lshl_add_u64 v[58:59], v[56:57], 0, v[58:59]
	v_ashrrev_i32_e32 v233, 31, v232
	global_load_dwordx4 v[172:175], v[58:59], off nt
	global_load_dwordx4 v[168:171], v[58:59], off offset:256 nt
	v_lshlrev_b64 v[58:59], 13, v[232:233]
	v_add_u32_e32 v234, 0xa0, v222
	v_lshl_add_u64 v[58:59], v[56:57], 0, v[58:59]
	v_ashrrev_i32_e32 v235, 31, v234
	global_load_dwordx4 v[164:167], v[58:59], off nt
	global_load_dwordx4 v[160:163], v[58:59], off offset:256 nt
	v_lshlrev_b64 v[58:59], 13, v[234:235]
	v_add_u32_e32 v236, 0xb0, v222
	v_lshl_add_u64 v[58:59], v[56:57], 0, v[58:59]
	v_ashrrev_i32_e32 v237, 31, v236
	global_load_dwordx4 v[156:159], v[58:59], off nt
	global_load_dwordx4 v[152:155], v[58:59], off offset:256 nt
	v_lshlrev_b64 v[58:59], 13, v[236:237]
	v_lshl_add_u64 v[56:57], v[56:57], 0, v[58:59]
	v_lshl_add_u64 v[60:61], v[220:221], 2, s[44:45]
	global_load_dwordx4 v[148:151], v[56:57], off nt
	global_load_dwordx4 v[144:147], v[56:57], off offset:256 nt
	global_load_dwordx4 v[64:67], v[60:61], off offset:16 nt
	global_load_dwordx4 v[68:71], v[60:61], off nt
	s_nop 0
	global_load_dwordx4 v[56:59], v[60:61], off offset:528 nt
	s_nop 0
	global_load_dwordx4 v[60:63], v[60:61], off offset:512 nt
	v_and_b32_e32 v248, 64, v244
	v_xor_b32_e32 v247, 16, v244
	v_add_u32_e32 v248, 64, v248
	v_cmp_lt_i32_e32 vcc, v247, v248
	v_xor_b32_e32 v249, 32, v244
	s_waitcnt vmcnt(0)
	v_lshlrev_b32_e32 v250, 16, v204
	v_and_b32_e32 v251, 0xffff0000, v204
	v_lshlrev_b32_e32 v204, 16, v205
	v_and_b32_e32 v205, 0xffff0000, v205
	v_pk_add_f32 v[142:143], v[142:143], v[204:205]
	v_pk_add_f32 v[140:141], v[140:141], v[250:251]
	v_lshlrev_b32_e32 v252, 16, v206
	v_and_b32_e32 v253, 0xffff0000, v206
	v_mul_f32_e32 v204, v141, v141
	v_mul_f32_e32 v205, v143, v143
	v_pk_add_f32 v[136:137], v[136:137], v[252:253]
	v_fmac_f32_e32 v204, v140, v140
	v_fmac_f32_e32 v205, v142, v142
	v_lshlrev_b32_e32 v206, 16, v207
	v_and_b32_e32 v207, 0xffff0000, v207
	v_add_f32_e32 v204, v204, v205
	v_mul_f32_e32 v205, v137, v137
	v_pk_add_f32 v[138:139], v[138:139], v[206:207]
	v_fmac_f32_e32 v205, v136, v136
	v_add_f32_e32 v204, v205, v204
	v_mul_f32_e32 v205, v139, v139
	v_cndmask_b32_e32 v247, v244, v247, vcc
	v_cmp_lt_i32_e32 vcc, v249, v248
	v_fmac_f32_e32 v205, v138, v138
	v_lshlrev_b32_e32 v206, 16, v202
	v_cndmask_b32_e32 v248, v244, v249, vcc
	v_add_f32_e32 v249, v205, v204
	v_lshlrev_b32_e32 v204, 16, v200
	v_and_b32_e32 v205, 0xffff0000, v200
	v_lshlrev_b32_e32 v200, 16, v201
	v_and_b32_e32 v201, 0xffff0000, v201
	v_pk_add_f32 v[134:135], v[134:135], v[200:201]
	v_pk_add_f32 v[132:133], v[132:133], v[204:205]
	v_and_b32_e32 v207, 0xffff0000, v202
	v_mul_f32_e32 v200, v133, v133
	v_mul_f32_e32 v201, v135, v135
	v_pk_add_f32 v[128:129], v[128:129], v[206:207]
	v_fmac_f32_e32 v200, v132, v132
	v_fmac_f32_e32 v201, v134, v134
	v_lshlrev_b32_e32 v202, 16, v203
	v_and_b32_e32 v203, 0xffff0000, v203
	v_add_f32_e32 v200, v200, v201
	v_mul_f32_e32 v201, v129, v129
	v_pk_add_f32 v[130:131], v[130:131], v[202:203]
	v_fmac_f32_e32 v201, v128, v128
	v_add_f32_e32 v200, v201, v200
	v_mul_f32_e32 v201, v131, v131
	v_fmac_f32_e32 v201, v130, v130
	v_add_f32_e32 v200, v201, v200
	v_lshlrev_b32_e32 v247, 2, v247
	v_add_f32_e32 v200, v249, v200
	ds_bpermute_b32 v201, v247, v200
	v_lshlrev_b32_e32 v248, 2, v248
	s_waitcnt lgkmcnt(0)
	v_add_f32_e32 v202, v200, v201
	ds_bpermute_b32 v203, v248, v202
	v_lshl_add_u64 v[200:201], v[222:223], 2, s[18:19]
	s_and_saveexec_b64 s[40:41], s[0:1]
	s_cbranch_execz .LBB0_820
	s_waitcnt lgkmcnt(0)
	v_add_f32_e32 v202, v202, v203
	global_atomic_add_f32 v[200:201], v202, off

.LBB0_849:
	s_or_b64 exec, exec, s[40:41]
	s_barrier
	global_load_dword v162, v211, s[10:11] sc1
	global_load_dword v163, v[200:201], off sc1
	global_load_dword v164, v[200:201], off offset:64 sc1
	global_load_dword v165, v[200:201], off offset:128 sc1
	global_load_dword v166, v[200:201], off offset:192 sc1
	global_load_dword v186, v[200:201], off offset:512 sc1
	global_load_dword v187, v[200:201], off offset:576 sc1
	global_load_dword v188, v[200:201], off offset:640 sc1
	global_load_dword v189, v[200:201], off offset:704 sc1
	v_lshlrev_b64 v[150:151], 12, v[222:223]
	v_lshlrev_b64 v[158:159], 12, v[224:225]
	v_lshlrev_b64 v[156:157], 12, v[226:227]
	v_lshl_add_u64 v[160:161], v[150:151], 2, s[64:65]
	v_lshlrev_b64 v[150:151], 2, v[220:221]
	v_lshl_add_u64 v[158:159], v[158:159], 2, s[64:65]
	v_lshl_add_u64 v[156:157], v[156:157], 2, s[64:65]
	v_lshl_add_u64 v[160:161], v[160:161], 0, v[150:151]
	v_lshlrev_b64 v[154:155], 12, v[228:229]
	v_lshl_add_u64 v[158:159], v[158:159], 0, v[150:151]
	v_lshl_add_u64 v[156:157], v[156:157], 0, v[150:151]
	v_lshlrev_b64 v[152:153], 12, v[230:231]
	v_lshlrev_b64 v[148:149], 12, v[232:233]
	v_lshlrev_b64 v[146:147], 12, v[234:235]
	v_lshlrev_b64 v[144:145], 12, v[236:237]
	s_waitcnt vmcnt(8)
	v_cmp_eq_u32_e32 vcc, 0, v162
	s_waitcnt vmcnt(7)
	v_fmamk_f32 v163, v163, 0x39800000, v245
	s_waitcnt vmcnt(6)
	v_fmamk_f32 v164, v164, 0x39800000, v245
	s_waitcnt vmcnt(5)
	v_fmamk_f32 v165, v165, 0x39800000, v245
	v_rsq_f32_e32 v163, v163
	v_rsq_f32_e32 v164, v164
	v_rsq_f32_e32 v165, v165
	s_waitcnt vmcnt(4)
	v_fmamk_f32 v166, v166, 0x39800000, v245
	v_rsq_f32_e32 v190, v166
	v_cndmask_b32_e32 v162, v246, v163, vcc
	v_cndmask_b32_e32 v164, v246, v164, vcc
	v_cndmask_b32_e32 v166, v246, v165, vcc
	v_pk_mul_f32 v[140:141], v[140:141], v[162:163] op_sel_hi:[1,0]
	v_pk_mul_f32 v[142:143], v[142:143], v[162:163] op_sel_hi:[1,0]
	v_pk_mul_f32 v[136:137], v[136:137], v[162:163] op_sel_hi:[1,0]
	v_pk_mul_f32 v[138:139], v[138:139], v[162:163] op_sel_hi:[1,0]
	v_pk_mul_f32 v[132:133], v[132:133], v[162:163] op_sel_hi:[1,0]
	v_pk_mul_f32 v[134:135], v[134:135], v[162:163] op_sel_hi:[1,0]
	v_pk_mul_f32 v[128:129], v[128:129], v[162:163] op_sel_hi:[1,0]
	v_pk_mul_f32 v[130:131], v[130:131], v[162:163] op_sel_hi:[1,0]
	v_pk_mul_f32 v[124:125], v[124:125], v[164:165] op_sel_hi:[1,0]
	v_pk_mul_f32 v[126:127], v[126:127], v[164:165] op_sel_hi:[1,0]
	v_pk_mul_f32 v[120:121], v[120:121], v[164:165] op_sel_hi:[1,0]
	v_pk_mul_f32 v[122:123], v[122:123], v[164:165] op_sel_hi:[1,0]
	v_pk_mul_f32 v[162:163], v[116:117], v[164:165] op_sel_hi:[1,0]
	v_pk_mul_f32 v[168:169], v[118:119], v[164:165] op_sel_hi:[1,0]
	v_pk_mul_f32 v[170:171], v[112:113], v[164:165] op_sel_hi:[1,0]
	v_pk_mul_f32 v[164:165], v[114:115], v[164:165] op_sel_hi:[1,0]
	v_pk_mul_f32 v[172:173], v[108:109], v[166:167] op_sel_hi:[1,0]
	v_pk_mul_f32 v[174:175], v[110:111], v[166:167] op_sel_hi:[1,0]
	v_pk_mul_f32 v[176:177], v[104:105], v[166:167] op_sel_hi:[1,0]
	v_pk_mul_f32 v[178:179], v[106:107], v[166:167] op_sel_hi:[1,0]
	v_pk_mul_f32 v[180:181], v[100:101], v[166:167] op_sel_hi:[1,0]
	v_pk_mul_f32 v[182:183], v[102:103], v[166:167] op_sel_hi:[1,0]
	v_pk_mul_f32 v[184:185], v[96:97], v[166:167] op_sel_hi:[1,0]
	v_pk_mul_f32 v[166:167], v[98:99], v[166:167] op_sel_hi:[1,0]
	v_pk_mul_f32 v[98:99], v[70:71], v[142:143]
	v_pk_mul_f32 v[96:97], v[68:69], v[140:141]
	v_pk_mul_f32 v[102:103], v[66:67], v[138:139]
	v_pk_mul_f32 v[100:101], v[64:65], v[136:137]
	v_pk_mul_f32 v[106:107], v[62:63], v[134:135]
	v_pk_mul_f32 v[104:105], v[60:61], v[132:133]
	v_pk_mul_f32 v[110:111], v[58:59], v[130:131]
	v_pk_mul_f32 v[108:109], v[56:57], v[128:129]
	v_pk_mul_f32 v[114:115], v[70:71], v[126:127]
	v_pk_mul_f32 v[112:113], v[68:69], v[124:125]
	v_pk_mul_f32 v[118:119], v[66:67], v[122:123]
	v_pk_mul_f32 v[116:117], v[64:65], v[120:121]
	v_pk_mul_f32 v[122:123], v[62:63], v[168:169]
	v_pk_mul_f32 v[120:121], v[60:61], v[162:163]
	v_pk_mul_f32 v[126:127], v[58:59], v[164:165]
	v_pk_mul_f32 v[124:125], v[56:57], v[170:171]
	v_pk_mul_f32 v[130:131], v[70:71], v[174:175]
	v_pk_mul_f32 v[128:129], v[68:69], v[172:173]
	v_pk_mul_f32 v[134:135], v[66:67], v[178:179]
	v_pk_mul_f32 v[132:133], v[64:65], v[176:177]
	v_pk_mul_f32 v[138:139], v[62:63], v[182:183]
	v_pk_mul_f32 v[136:137], v[60:61], v[180:181]
	v_pk_mul_f32 v[142:143], v[58:59], v[166:167]
	v_pk_mul_f32 v[140:141], v[56:57], v[184:185]
	global_store_dwordx4 v[160:161], v[96:99], off nt
	global_store_dwordx4 v[160:161], v[100:103], off offset:16 nt
	global_store_dwordx4 v[160:161], v[104:107], off offset:512 nt
	global_store_dwordx4 v[160:161], v[108:111], off offset:528 nt
	global_store_dwordx4 v[158:159], v[112:115], off nt
	global_store_dwordx4 v[158:159], v[116:119], off offset:16 nt
	global_store_dwordx4 v[158:159], v[120:123], off offset:512 nt
	global_store_dwordx4 v[158:159], v[124:127], off offset:528 nt
	global_store_dwordx4 v[156:157], v[128:131], off nt
	global_store_dwordx4 v[156:157], v[132:135], off offset:16 nt
	global_store_dwordx4 v[156:157], v[136:139], off offset:512 nt
	global_store_dwordx4 v[156:157], v[140:143], off offset:528 nt
	v_cndmask_b32_e32 v96, v246, v190, vcc
	v_pk_mul_f32 v[92:93], v[92:93], v[96:97] op_sel_hi:[1,0]
	v_pk_mul_f32 v[94:95], v[94:95], v[96:97] op_sel_hi:[1,0]
	v_pk_mul_f32 v[88:89], v[88:89], v[96:97] op_sel_hi:[1,0]
	v_lshl_add_u64 v[98:99], v[154:155], 2, s[64:65]
	v_pk_mul_f32 v[94:95], v[70:71], v[94:95]
	v_pk_mul_f32 v[92:93], v[68:69], v[92:93]
	v_pk_mul_f32 v[90:91], v[90:91], v[96:97] op_sel_hi:[1,0]
	v_pk_mul_f32 v[88:89], v[64:65], v[88:89]
	v_lshl_add_u64 v[98:99], v[98:99], 0, v[150:151]
	v_pk_mul_f32 v[90:91], v[66:67], v[90:91]
	global_store_dwordx4 v[98:99], v[92:95], off nt
	global_store_dwordx4 v[98:99], v[88:91], off offset:16 nt
	v_pk_mul_f32 v[84:85], v[84:85], v[96:97] op_sel_hi:[1,0]
	v_pk_mul_f32 v[86:87], v[86:87], v[96:97] op_sel_hi:[1,0]
	s_waitcnt vmcnt(17)
	v_fmamk_f32 v88, v186, 0x39800000, v245
	v_rsq_f32_e32 v88, v88
	v_pk_mul_f32 v[80:81], v[80:81], v[96:97] op_sel_hi:[1,0]
	v_pk_mul_f32 v[86:87], v[62:63], v[86:87]
	v_pk_mul_f32 v[84:85], v[60:61], v[84:85]
	v_pk_mul_f32 v[82:83], v[82:83], v[96:97] op_sel_hi:[1,0]
	v_pk_mul_f32 v[80:81], v[56:57], v[80:81]
	v_pk_mul_f32 v[82:83], v[58:59], v[82:83]
	global_store_dwordx4 v[98:99], v[84:87], off offset:512 nt
	global_store_dwordx4 v[98:99], v[80:83], off offset:528 nt
	s_nop 1
	v_cndmask_b32_e32 v80, v246, v88, vcc
	v_pk_mul_f32 v[76:77], v[76:77], v[80:81] op_sel_hi:[1,0]
	v_pk_mul_f32 v[78:79], v[78:79], v[80:81] op_sel_hi:[1,0]
	v_pk_mul_f32 v[72:73], v[72:73], v[80:81] op_sel_hi:[1,0]
	v_lshl_add_u64 v[82:83], v[152:153], 2, s[64:65]
	v_pk_mul_f32 v[78:79], v[70:71], v[78:79]
	v_pk_mul_f32 v[76:77], v[68:69], v[76:77]
	v_pk_mul_f32 v[74:75], v[74:75], v[80:81] op_sel_hi:[1,0]
	v_pk_mul_f32 v[72:73], v[64:65], v[72:73]
	v_lshl_add_u64 v[82:83], v[82:83], 0, v[150:151]
	v_pk_mul_f32 v[74:75], v[66:67], v[74:75]
	global_store_dwordx4 v[82:83], v[76:79], off nt
	global_store_dwordx4 v[82:83], v[72:75], off offset:16 nt
	v_pk_mul_f32 v[52:53], v[52:53], v[80:81] op_sel_hi:[1,0]
	v_pk_mul_f32 v[54:55], v[54:55], v[80:81] op_sel_hi:[1,0]
	s_waitcnt vmcnt(20)
	v_fmamk_f32 v72, v187, 0x39800000, v245
	v_rsq_f32_e32 v72, v72
	v_pk_mul_f32 v[48:49], v[48:49], v[80:81] op_sel_hi:[1,0]
	v_pk_mul_f32 v[54:55], v[62:63], v[54:55]
	v_pk_mul_f32 v[52:53], v[60:61], v[52:53]
	v_pk_mul_f32 v[50:51], v[50:51], v[80:81] op_sel_hi:[1,0]
	v_pk_mul_f32 v[48:49], v[56:57], v[48:49]
	v_pk_mul_f32 v[50:51], v[58:59], v[50:51]
	global_store_dwordx4 v[82:83], v[52:55], off offset:512 nt
	global_store_dwordx4 v[82:83], v[48:51], off offset:528 nt
	s_nop 1
	v_cndmask_b32_e32 v48, v246, v72, vcc
	v_pk_mul_f32 v[44:45], v[44:45], v[48:49] op_sel_hi:[1,0]
	v_pk_mul_f32 v[46:47], v[46:47], v[48:49] op_sel_hi:[1,0]
	v_pk_mul_f32 v[40:41], v[40:41], v[48:49] op_sel_hi:[1,0]
	v_lshl_add_u64 v[50:51], v[148:149], 2, s[64:65]
	v_pk_mul_f32 v[46:47], v[70:71], v[46:47]
	v_pk_mul_f32 v[44:45], v[68:69], v[44:45]
	v_pk_mul_f32 v[42:43], v[42:43], v[48:49] op_sel_hi:[1,0]
	v_pk_mul_f32 v[40:41], v[64:65], v[40:41]
	v_lshl_add_u64 v[50:51], v[50:51], 0, v[150:151]
	v_pk_mul_f32 v[42:43], v[66:67], v[42:43]
	global_store_dwordx4 v[50:51], v[44:47], off nt
	global_store_dwordx4 v[50:51], v[40:43], off offset:16 nt
	v_pk_mul_f32 v[36:37], v[36:37], v[48:49] op_sel_hi:[1,0]
	v_pk_mul_f32 v[38:39], v[38:39], v[48:49] op_sel_hi:[1,0]
	s_waitcnt vmcnt(23)
	v_fmamk_f32 v40, v188, 0x39800000, v245
	v_rsq_f32_e32 v40, v40
	v_pk_mul_f32 v[32:33], v[32:33], v[48:49] op_sel_hi:[1,0]
	v_pk_mul_f32 v[38:39], v[62:63], v[38:39]
	v_pk_mul_f32 v[36:37], v[60:61], v[36:37]
	v_pk_mul_f32 v[34:35], v[34:35], v[48:49] op_sel_hi:[1,0]
	v_pk_mul_f32 v[32:33], v[56:57], v[32:33]
	v_pk_mul_f32 v[34:35], v[58:59], v[34:35]
	global_store_dwordx4 v[50:51], v[36:39], off offset:512 nt
	global_store_dwordx4 v[50:51], v[32:35], off offset:528 nt
	s_nop 1
	v_cndmask_b32_e32 v32, v246, v40, vcc
	v_pk_mul_f32 v[28:29], v[28:29], v[32:33] op_sel_hi:[1,0]
	v_pk_mul_f32 v[30:31], v[30:31], v[32:33] op_sel_hi:[1,0]
	v_pk_mul_f32 v[24:25], v[24:25], v[32:33] op_sel_hi:[1,0]
	v_lshl_add_u64 v[34:35], v[146:147], 2, s[64:65]
	v_pk_mul_f32 v[30:31], v[70:71], v[30:31]
	v_pk_mul_f32 v[28:29], v[68:69], v[28:29]
	v_pk_mul_f32 v[26:27], v[26:27], v[32:33] op_sel_hi:[1,0]
	v_pk_mul_f32 v[24:25], v[64:65], v[24:25]
	v_lshl_add_u64 v[34:35], v[34:35], 0, v[150:151]
	v_pk_mul_f32 v[26:27], v[66:67], v[26:27]
	global_store_dwordx4 v[34:35], v[28:31], off nt
	global_store_dwordx4 v[34:35], v[24:27], off offset:16 nt
	v_pk_mul_f32 v[20:21], v[20:21], v[32:33] op_sel_hi:[1,0]
	v_pk_mul_f32 v[22:23], v[22:23], v[32:33] op_sel_hi:[1,0]
	s_waitcnt vmcnt(26)
	v_fmamk_f32 v24, v189, 0x39800000, v245
	v_rsq_f32_e32 v24, v24
	v_pk_mul_f32 v[16:17], v[16:17], v[32:33] op_sel_hi:[1,0]
	v_pk_mul_f32 v[22:23], v[62:63], v[22:23]
	v_pk_mul_f32 v[20:21], v[60:61], v[20:21]
	v_pk_mul_f32 v[18:19], v[18:19], v[32:33] op_sel_hi:[1,0]
	v_pk_mul_f32 v[16:17], v[56:57], v[16:17]
	v_pk_mul_f32 v[18:19], v[58:59], v[18:19]
	global_store_dwordx4 v[34:35], v[20:23], off offset:512 nt
	global_store_dwordx4 v[34:35], v[16:19], off offset:528 nt
	s_nop 1
	v_cndmask_b32_e32 v16, v246, v24, vcc
	v_pk_mul_f32 v[12:13], v[12:13], v[16:17] op_sel_hi:[1,0]
	v_pk_mul_f32 v[14:15], v[14:15], v[16:17] op_sel_hi:[1,0]
	v_lshl_add_u64 v[18:19], v[144:145], 2, s[64:65]
	v_pk_mul_f32 v[4:5], v[4:5], v[16:17] op_sel_hi:[1,0]
	v_pk_mul_f32 v[6:7], v[6:7], v[16:17] op_sel_hi:[1,0]
	v_pk_mul_f32 v[14:15], v[70:71], v[14:15]
	v_pk_mul_f32 v[12:13], v[68:69], v[12:13]
	v_pk_mul_f32 v[8:9], v[8:9], v[16:17] op_sel_hi:[1,0]
	v_pk_mul_f32 v[10:11], v[10:11], v[16:17] op_sel_hi:[1,0]
	v_lshl_add_u64 v[18:19], v[18:19], 0, v[150:151]
	v_pk_mul_f32 v[6:7], v[62:63], v[6:7]
	v_pk_mul_f32 v[4:5], v[60:61], v[4:5]
	v_pk_mul_f32 v[0:1], v[0:1], v[16:17] op_sel_hi:[1,0]
	v_pk_mul_f32 v[2:3], v[2:3], v[16:17] op_sel_hi:[1,0]
	s_andn2_b64 vcc, exec, s[4:5]
	s_mov_b64 s[4:5], -1
	v_pk_mul_f32 v[10:11], v[66:67], v[10:11]
	v_pk_mul_f32 v[8:9], v[64:65], v[8:9]
	global_store_dwordx4 v[18:19], v[12:15], off nt
	global_store_dwordx4 v[18:19], v[8:11], off offset:16 nt
	v_pk_mul_f32 v[2:3], v[58:59], v[2:3]
	v_pk_mul_f32 v[0:1], v[56:57], v[0:1]
	global_store_dwordx4 v[18:19], v[4:7], off offset:512 nt
	global_store_dwordx4 v[18:19], v[0:3], off offset:528 nt
	s_cbranch_vccnz .LBB0_806
	s_andn2_b64 vcc, exec, s[8:9]
	s_cbranch_vccnz .LBB0_805
	s_barrier
	s_branch .LBB0_805
